# flips deleted + one static s_setprio 1 for waves 4-7 at kernel entry
# baseline (speedup 1.0000x reference)
; #define LAS __attribute__((address_space(3)))
; __device__ __forceinline__ unsigned xb_add(unsigned* p, unsigned v) { return __hip_atomic_fetch_add(p, v, __ATOMIC_RELAXED, __HIP_MEMORY_SCOPE_AGENT); }
; __device__ __forceinline__ unsigned xb_xcc_id() { return (unsigned)__builtin_amdgcn_s_getreg((3 << 11) | 20) & 0xFu; }
; #define LOADP(Pl) Params Pl; { CParams q_ = pk; asm volatile("" : "+s"(q_)); Pl = *q_; }
; __device__ __forceinline__ XcdBarrier xcd_barrier_post(unsigned* bar, volatile LAS unsigned* st) {
;     XcdBarrier b; b.bar = bar; b.x = xb_xcc_id(); b.st = st;
;     if (threadIdx.x == 0) (void)xb_add(&bar[XB_XCNT(b.x)], 1u);
;     return b;
; __global__ void __launch_bounds__(512) fwd_megakernel(Params Parg) {
;     ...
;     if (threadIdx.x == 0) { xst[0] = 0u; xst[1] = 0u; }
;     __syncthreads();
;     XcdBarrier xb; { LOADP(P) xb = xcd_barrier_post((unsigned*)(P.ws + OFF_BAR), xst); }
.LBB0_2:
	s_or_b64 exec, exec, s[8:9]
	v_readfirstlane_b32 vcc_lo, v186
	s_cmpk_gt_u32 vcc_lo, 0xff
	s_cbranch_scc0 .Lprio_static_done
	s_setprio 1
.Lprio_static_done:
	s_mov_b64 s[2:3], s[0:1]
	s_waitcnt lgkmcnt(0)
	s_barrier
	s_load_dwordx2 s[66:67], s[2:3], 0xd0
	s_getreg_b32 s8, hwreg(HW_REG_XCC_ID, 0, 4)
	s_waitcnt lgkmcnt(0)
	s_add_u32 s2, s66, 0x21000000
	s_addc_u32 s3, s67, 0
	s_and_b32 s54, s8, 15
	s_mov_b64 s[8:9], exec
	v_readlane_b32 s10, v233, 0
	v_readlane_b32 s11, v233, 1
	s_and_b64 s[10:11], s[8:9], s[10:11]
	s_mov_b64 exec, s[10:11]
	s_cbranch_execz .LBB0_5
	s_mov_b64 s[10:11], exec
	v_mbcnt_lo_u32_b32 v1, s10, 0
	v_mbcnt_hi_u32_b32 v1, s11, v1
	v_cmp_eq_u32_e32 vcc, 0, v1
	s_and_b64 s[12:13], exec, vcc
	s_mov_b64 exec, s[12:13]
	s_cbranch_execz .LBB0_5
	s_lshl_b32 s12, s54, 8
	s_bcnt1_i32_b64 s10, s[10:11]
	v_mov_b32_e32 v1, s12
	v_mov_b32_e32 v2, s10
	global_atomic_add v1, v2, s[2:3] offset:1024
